# sample attention: key entries visited in distance order (LDS permutation table) so the rows shared by the three dilated patterns are fetched once per batch; on top of v11
# baseline (speedup 1.0000x reference)
; #define GRID_BAR() xcd_barrier(bar)
; __global__ void __launch_bounds__(NWAVES * 64, 2) mega_fwd(Args args) {
;     ...
;     for (int unit = gw; unit < NB * NH * gdn::NCH; unit += NGW) gdn::pre_unit(unit, P, (const unsigned short*)(ws + WS_PB), in[14], in[15], in[16], REC, L + RING_OFF + wave * 16384, lane);
;     GRID_BAR();
;     if (vcu < NB * NH) gdn::scan_wg(vcu, REC, (const unsigned short*)(ws + WS_PB), in[17], HEADS, out + O_SGP, L + RING_OFF, tid);
.LBB0_1129:
	s_or_b64 exec, exec, s[0:1]
	v_readlane_b32 s0, v244, 24
	v_readlane_b32 s1, v244, 25
	s_add_u32 s42, s0, 0x24c00000
	s_addc_u32 s43, s1, 0
	v_readlane_b32 s0, v244, 0
	s_cmp_lt_i32 s0, 64
	s_waitcnt lgkmcnt(0)
	s_barrier
	v_readlane_b32 s1, v244, 1
	s_mov_b32 s101, 0x20400
	v_and_b32_e32 v246, 0x3ff, v0
	v_cmp_lt_u32_e32 vcc, 0x80, v246
	s_nop 1
	v_cndmask_b32_e64 v247, 0, 1, vcc
	v_cmp_lt_u32_e32 vcc, 0x101, v246
	s_nop 1
	v_cndmask_b32_e64 v248, 0, 1, vcc
	v_add_u32_e32 v247, v247, v248
	v_mul_u32_u24_e32 v249, 0x81, v247
	v_sub_u32_e32 v249, v246, v249
	v_lshlrev_b32_e32 v250, 1, v247
	v_lshlrev_b32_e32 v249, v250, v249
	v_min_u32_e32 v251, 1, v247
	v_add_u32_e32 v251, v249, v251
	v_max_u32_e32 v251, 32, v251
	v_min_u32_e32 v251, 0x81, v251
	v_subrev_u32_e32 v251, 32, v251
	v_add_u32_e32 v252, v249, v248
	v_add_u32_e32 v252, 3, v252
	v_lshrrev_b32_e32 v252, 2, v252
	v_min_u32_e32 v252, 0x81, v252
	v_add_u32_e32 v253, 15, v249
	v_lshrrev_b32_e32 v253, 4, v253
	v_min_u32_e32 v253, 0x81, v253
	v_add3_u32 v251, v251, v252, v253
	v_add_u32_e32 v251, 32, v251
	v_cmp_gt_u32_e32 vcc, 32, v246
	s_nop 1
	v_cndmask_b32_e32 v251, v251, v246, vcc
	v_cmp_lt_u32_e32 vcc, 0x182, v246
	s_nop 1
	v_cndmask_b32_e32 v251, v251, v246, vcc
	v_cmp_gt_u32_e32 vcc, 0x188, v246
	s_and_saveexec_b64 s[98:99], vcc
	v_lshl_add_u32 v252, v251, 2, s101
	ds_write_b32 v252, v246
	s_or_b64 exec, exec, s[98:99]
	s_waitcnt lgkmcnt(0)
	s_barrier
	s_cmp_lt_i32 s0, 64
	s_cbranch_scc0 .LBB0_1220
	v_mov_b32_e32 v114, v0
	v_readlane_b32 s0, v245, 39
	v_lshlrev_b32_e32 v2, 2, v114
	v_and_b32_e32 v112, 60, v2
	v_lshlrev_b32_e32 v86, 2, v112
	v_readlane_b32 s2, v245, 41
	v_readlane_b32 s3, v245, 42
	s_barrier
	v_readlane_b32 s1, v245, 40
	v_readfirstlane_b32 s0, v114
	s_nop 1
	global_load_dwordx4 v[66:69], v86, s[2:3]
	s_ashr_i32 s26, s0, 6
	v_readlane_b32 s0, v244, 0
	v_readlane_b32 s1, v244, 1
	s_mov_b32 s2, s0
	s_ashr_i32 s3, s0, 31
	s_ashr_i32 s35, s0, 3
	s_and_b32 s27, s0, 7
	v_writelane_b32 v244, s2, 0
	s_mul_i32 s1, s2, 0x168000
	s_mul_hi_i32 s0, s0, 0x168000
	s_add_u32 s30, s44, s1
	s_addc_u32 s31, s45, s0
	s_add_i32 s34, s26, -2
	v_add_u32_e32 v104, 0xffffff80, v114
	s_cmp_gt_u32 s34, 2
	v_mov_b32_e32 v83, 0
	v_readlane_b32 s4, v245, 43
	v_readlane_b32 s5, v245, 44
	v_readlane_b32 s6, v245, 45
	v_readlane_b32 s7, v245, 46
	v_readlane_b32 s8, v245, 47
	v_readlane_b32 s9, v245, 48
	v_readlane_b32 s10, v245, 49
	v_readlane_b32 s11, v245, 50
	v_readlane_b32 s12, v245, 51
	v_readlane_b32 s13, v245, 52
	v_readlane_b32 s14, v245, 53
	v_readlane_b32 s15, v245, 54
	v_writelane_b32 v244, s3, 1
	s_cbranch_scc1 .LBB0_1152
	v_min_i32_e32 v2, 0x59f, v104
	v_ashrrev_i32_e32 v3, 31, v2
	v_lshlrev_b64 v[84:85], 4, v[2:3]
	v_min_i32_e32 v2, 0x4df, v104
	v_ashrrev_i32_e32 v3, 31, v2
	v_mov_b64_e32 v[4:5], 0xc00
	v_min_i32_e32 v6, 0x41f, v104
	v_lshl_add_u64 v[2:3], v[2:3], 4, v[4:5]
	v_ashrrev_i32_e32 v7, 31, v6
	v_mov_b64_e32 v[8:9], 0x1800
	v_lshl_add_u64 v[4:5], s[30:31], 0, v[2:3]
	v_lshl_add_u64 v[6:7], v[6:7], 4, v[8:9]
	v_lshl_add_u64 v[8:9], s[30:31], 0, v[6:7]
	global_load_dwordx4 v[74:77], v[4:5], off
	global_load_dwordx4 v[54:57], v[8:9], off
	v_min_i32_e32 v4, 0x35f, v104
	v_ashrrev_i32_e32 v5, 31, v4
	v_mov_b64_e32 v[8:9], 0x2400
	v_min_i32_e32 v10, 0x29f, v104
	v_lshl_add_u64 v[4:5], v[4:5], 4, v[8:9]
	v_ashrrev_i32_e32 v11, 31, v10
	v_mov_b64_e32 v[12:13], 0x3000
	s_lshl_b32 s0, s35, 11
	v_lshl_add_u64 v[8:9], s[30:31], 0, v[4:5]
	v_lshl_add_u64 v[10:11], v[10:11], 4, v[12:13]
	s_ashr_i32 s1, s0, 31
	v_lshl_add_u64 v[12:13], s[30:31], 0, v[10:11]
	global_load_dwordx4 v[62:65], v[8:9], off
	global_load_dwordx4 v[46:49], v[12:13], off
	v_min_i32_e32 v8, 0x1df, v104
	s_lshl_b64 s[2:3], s[0:1], 12
	v_ashrrev_i32_e32 v9, 31, v8
	v_mov_b64_e32 v[12:13], 0x3c00
	v_min_i32_e32 v14, 0x11f, v104
	s_add_u32 s1, s64, s2
	v_lshl_add_u64 v[8:9], v[8:9], 4, v[12:13]
	v_ashrrev_i32_e32 v15, 31, v14
	v_mov_b64_e32 v[16:17], 0x4800
	v_min_i32_e32 v20, 0xff, v104
	s_addc_u32 s3, s65, s3
	v_lshl_add_u64 v[12:13], s[30:31], 0, v[8:9]
	v_lshl_add_u64 v[14:15], v[14:15], 4, v[16:17]
	s_lshl_b32 s4, s27, 7
	v_ashrrev_i32_e32 v18, 3, v20
	v_lshl_add_u64 v[16:17], s[30:31], 0, v[14:15]
	global_load_dwordx4 v[58:61], v[12:13], off
	global_load_dwordx4 v[42:45], v[16:17], off
	v_min_i32_e32 v12, 0x5f, v104
	s_add_u32 s2, s1, s4
	v_ashrrev_i32_e32 v19, 31, v18
	v_ashrrev_i32_e32 v13, 31, v12
	v_mov_b64_e32 v[16:17], 0x5400
	s_addc_u32 s3, s3, 0
	v_lshlrev_b64 v[88:89], 12, v[18:19]
	v_lshlrev_b32_e32 v20, 4, v20
	v_lshl_add_u64 v[12:13], v[12:13], 4, v[16:17]
	v_lshl_add_u64 v[18:19], s[2:3], 0, v[88:89]
	v_and_b32_e32 v82, 0x70, v20
	v_lshl_add_u64 v[16:17], s[30:31], 0, v[12:13]
	v_lshl_add_u64 v[18:19], v[18:19], 0, v[82:83]
	global_load_dwordx4 v[70:73], v[16:17], off
	global_load_dwordx4 v[50:53], v[18:19], off offset:3072
	v_min_i32_e32 v18, 63, v104
	v_add_u32_e32 v16, 0xc0, v18
	v_ashrrev_i32_e32 v16, 3, v16
	v_ashrrev_i32_e32 v17, 31, v16
	v_lshlrev_b64 v[90:91], 12, v[16:17]
	v_lshl_add_u64 v[16:17], s[2:3], 0, v[90:91]
	s_add_u32 s2, s30, 0x5a00
	s_addc_u32 s3, s31, 0
	s_or_b32 s0, s0, 32
	s_ashr_i32 s1, s0, 31
	v_lshlrev_b32_e32 v18, 4, v18
	s_lshl_b64 s[0:1], s[0:1], 12
	v_and_b32_e32 v92, 0x70, v18
	v_mov_b32_e32 v93, v83
	s_add_u32 s0, s64, s0
	v_lshl_add_u64 v[16:17], v[16:17], 0, v[92:93]
	s_addc_u32 s1, s65, s1
	v_lshl_add_u64 v[2:3], s[2:3], 0, v[2:3]
	v_lshl_add_u64 v[18:19], s[2:3], 0, v[84:85]
	global_load_dwordx4 v[78:81], v[16:17], off offset:3072
	global_load_dwordx4 v[38:41], v[18:19], off
	v_lshl_add_u64 v[6:7], s[2:3], 0, v[6:7]
	global_load_dwordx4 v[34:37], v[2:3], off
	global_load_dwordx4 v[30:33], v[6:7], off
	v_lshl_add_u64 v[2:3], s[2:3], 0, v[4:5]
	v_lshl_add_u64 v[4:5], s[2:3], 0, v[10:11]
	s_add_u32 s0, s0, s4
	global_load_dwordx4 v[26:29], v[2:3], off
	global_load_dwordx4 v[22:25], v[4:5], off
	v_lshl_add_u64 v[2:3], s[2:3], 0, v[8:9]
	v_lshl_add_u64 v[4:5], s[2:3], 0, v[14:15]
	s_addc_u32 s1, s1, 0
	global_load_dwordx4 v[18:21], v[2:3], off
	global_load_dwordx4 v[14:17], v[4:5], off
	v_lshl_add_u64 v[2:3], s[2:3], 0, v[12:13]
	v_lshl_add_u64 v[4:5], s[0:1], 0, v[88:89]
	v_lshl_add_u64 v[4:5], v[4:5], 0, v[82:83]
	global_load_dwordx4 v[10:13], v[2:3], off
	global_load_dwordx4 v[6:9], v[4:5], off offset:3072
	v_lshl_add_u64 v[2:3], s[0:1], 0, v[90:91]
	v_lshl_add_u64 v[2:3], v[2:3], 0, v[92:93]
	global_load_dwordx4 v[2:5], v[2:3], off offset:3072
	s_movk_i32 s0, 0x620
	v_cmp_gt_i32_e32 vcc, s0, v114
	v_lshl_add_u32 v82, v104, 4, 0
	s_and_saveexec_b64 s[0:1], vcc
	s_cbranch_execz .LBB0_1133
	v_lshl_add_u64 v[84:85], s[30:31], 0, v[84:85]
	global_load_dwordx4 v[88:91], v[84:85], off
	s_waitcnt vmcnt(0)
	ds_write_b128 v82, v[88:91]

.LBB0_1251:
	v_subrev_u32_e32 v66, 56, v223
	v_min_i32_e32 v255, 0x187, v66
	v_lshl_add_u32 v255, v255, 2, s101
	ds_read_b32 v66, v255
	s_waitcnt lgkmcnt(0)
	v_cmp_lt_i32_e32 vcc, s19, v66
	v_min_i32_e32 v54, 0x182, v66
	s_nop 0
	v_cndmask_b32_e64 v55, 0, 1, vcc
	v_cmp_gt_i32_e32 vcc, s24, v66
	s_nop 1
	v_cndmask_b32_e32 v55, 2, v55, vcc
	v_mul_i32_i24_e32 v56, 0xffffff7f, v55
	v_lshlrev_b32_e32 v55, 1, v55
	v_add_lshl_u32 v54, v56, v54, v55
	v_sub_u32_e32 v156, s18, v54
	v_cmp_lt_i32_e32 vcc, s25, v156
	v_cmp_gt_i32_e64 s[0:1], s17, v156
	s_and_saveexec_b64 s[14:15], s[0:1]
	s_xor_b64 s[0:1], exec, s[14:15]
	v_ashrrev_i32_e32 v55, 31, v156
	v_mov_b32_e32 v54, v156
	v_lshlrev_b64 v[56:57], 11, v[54:55]
	v_lshl_add_u64 v[54:55], v[194:195], 0, v[56:57]
	s_andn2_saveexec_b64 s[0:1], s[0:1]
	v_add_u32_e32 v54, 0xfffff800, v156
	v_mad_u64_u32 v[54:55], s[14:15], v54, s26, v[198:199]
	v_lshlrev_b64 v[56:57], 11, v[156:157]
	s_or_b64 exec, exec, s[0:1]
	v_lshl_add_u64 v[62:63], v[54:55], 0, s[38:39]
	v_lshl_add_u64 v[56:57], v[200:201], 0, v[56:57]
	v_cndmask_b32_e32 v63, v57, v63, vcc
	v_cndmask_b32_e32 v62, v56, v62, vcc
	v_min_i32_e32 v66, 0x187, v66
	global_load_dwordx4 v[102:105], v[54:55], off offset:16
	global_load_dwordx4 v[114:117], v[54:55], off
	s_nop 0
	global_load_dwordx4 v[54:57], v[62:63], off offset:16
	s_nop 0
	global_load_dwordx4 v[62:65], v[62:63], off
	v_ashrrev_i32_e32 v67, 31, v66
	v_lshl_add_u64 v[66:67], v[66:67], 2, s[40:41]
	global_load_dword v229, v[66:67], off
	v_subrev_u32_e32 v82, 48, v223
	v_min_i32_e32 v255, 0x187, v82
	v_lshl_add_u32 v255, v255, 2, s101
	ds_read_b32 v82, v255
	s_waitcnt lgkmcnt(0)
	v_cmp_lt_i32_e32 vcc, s19, v82
	v_min_i32_e32 v66, 0x182, v82
	s_nop 0
	v_cndmask_b32_e64 v67, 0, 1, vcc
	v_cmp_gt_i32_e32 vcc, s24, v82
	s_nop 1
	v_cndmask_b32_e32 v67, 2, v67, vcc
	v_mul_i32_i24_e32 v68, 0xffffff7f, v67
	v_lshlrev_b32_e32 v67, 1, v67
	v_add_lshl_u32 v66, v68, v66, v67
	v_sub_u32_e32 v68, s18, v66
	v_cmp_lt_i32_e32 vcc, s25, v68
	v_cmp_gt_i32_e64 s[0:1], s17, v68
	s_and_saveexec_b64 s[14:15], s[0:1]
	s_xor_b64 s[0:1], exec, s[14:15]
	v_ashrrev_i32_e32 v69, 31, v68
	v_lshlrev_b64 v[78:79], 11, v[68:69]
	v_lshl_add_u64 v[66:67], v[194:195], 0, v[78:79]
	s_andn2_saveexec_b64 s[0:1], s[0:1]
	v_add_u32_e32 v66, 0xfffff800, v68
	v_mov_b32_e32 v69, v157
	v_mad_u64_u32 v[66:67], s[14:15], v66, s26, v[198:199]
	v_lshlrev_b64 v[78:79], 11, v[68:69]
	s_or_b64 exec, exec, s[0:1]
	v_lshl_add_u64 v[68:69], v[66:67], 0, s[38:39]
	v_lshl_add_u64 v[78:79], v[200:201], 0, v[78:79]
	v_cndmask_b32_e32 v79, v79, v69, vcc
	v_cndmask_b32_e32 v78, v78, v68, vcc
	v_min_i32_e32 v82, 0x187, v82
	global_load_dwordx4 v[118:121], v[66:67], off offset:16
	global_load_dwordx4 v[122:125], v[66:67], off
	s_nop 0
	global_load_dwordx4 v[66:69], v[78:79], off offset:16
	s_nop 0
	global_load_dwordx4 v[78:81], v[78:79], off
	v_ashrrev_i32_e32 v83, 31, v82
	v_lshl_add_u64 v[82:83], v[82:83], 2, s[40:41]
	global_load_dword v230, v[82:83], off
	v_subrev_u32_e32 v90, 40, v223
	v_min_i32_e32 v255, 0x187, v90
	v_lshl_add_u32 v255, v255, 2, s101
	ds_read_b32 v90, v255
	s_waitcnt lgkmcnt(0)
	v_cmp_lt_i32_e32 vcc, s19, v90
	v_min_i32_e32 v82, 0x182, v90
	s_nop 0
	v_cndmask_b32_e64 v83, 0, 1, vcc
	v_cmp_gt_i32_e32 vcc, s24, v90
	s_nop 1
	v_cndmask_b32_e32 v83, 2, v83, vcc
	v_mul_i32_i24_e32 v84, 0xffffff7f, v83
	v_lshlrev_b32_e32 v83, 1, v83
	v_add_lshl_u32 v82, v84, v82, v83
	v_sub_u32_e32 v84, s18, v82
	v_cmp_lt_i32_e32 vcc, s25, v84
	v_cmp_gt_i32_e64 s[0:1], s17, v84
	s_and_saveexec_b64 s[14:15], s[0:1]
	s_xor_b64 s[0:1], exec, s[14:15]
	v_ashrrev_i32_e32 v85, 31, v84
	v_lshlrev_b64 v[86:87], 11, v[84:85]
	v_lshl_add_u64 v[82:83], v[194:195], 0, v[86:87]
	s_andn2_saveexec_b64 s[0:1], s[0:1]
	v_add_u32_e32 v82, 0xfffff800, v84
	v_mov_b32_e32 v85, v157
	v_mad_u64_u32 v[82:83], s[14:15], v82, s26, v[198:199]
	v_lshlrev_b64 v[86:87], 11, v[84:85]
	s_or_b64 exec, exec, s[0:1]
	v_lshl_add_u64 v[84:85], v[82:83], 0, s[38:39]
	v_lshl_add_u64 v[86:87], v[200:201], 0, v[86:87]
	v_cndmask_b32_e32 v85, v87, v85, vcc
	v_cndmask_b32_e32 v84, v86, v84, vcc
	global_load_dwordx4 v[134:137], v[82:83], off offset:16
	global_load_dwordx4 v[138:141], v[82:83], off
	global_load_dwordx4 v[86:89], v[84:85], off offset:16
	global_load_dwordx4 v[94:97], v[84:85], off
	v_min_i32_e32 v82, 0x187, v90
	v_ashrrev_i32_e32 v83, 31, v82
	v_lshl_add_u64 v[82:83], v[82:83], 2, s[40:41]
	global_load_dword v231, v[82:83], off
	v_subrev_u32_e32 v92, 32, v223
	v_min_i32_e32 v255, 0x187, v92
	v_lshl_add_u32 v255, v255, 2, s101
	ds_read_b32 v92, v255
	s_waitcnt lgkmcnt(0)
	v_cmp_lt_i32_e32 vcc, s19, v92
	v_min_i32_e32 v82, 0x182, v92
	s_nop 0
	v_cndmask_b32_e64 v83, 0, 1, vcc
	v_cmp_gt_i32_e32 vcc, s24, v92
	s_nop 1
	v_cndmask_b32_e32 v83, 2, v83, vcc
	v_mul_i32_i24_e32 v84, 0xffffff7f, v83
	v_lshlrev_b32_e32 v83, 1, v83
	v_add_lshl_u32 v82, v84, v82, v83
	v_sub_u32_e32 v84, s18, v82
	v_cmp_lt_i32_e32 vcc, s25, v84
	v_cmp_gt_i32_e64 s[0:1], s17, v84
	s_and_saveexec_b64 s[14:15], s[0:1]
	s_xor_b64 s[0:1], exec, s[14:15]
	v_ashrrev_i32_e32 v85, 31, v84
	v_lshlrev_b64 v[90:91], 11, v[84:85]
	v_lshl_add_u64 v[82:83], v[194:195], 0, v[90:91]
	s_andn2_saveexec_b64 s[0:1], s[0:1]
	v_add_u32_e32 v82, 0xfffff800, v84
	v_mov_b32_e32 v85, v157
	v_mad_u64_u32 v[82:83], s[14:15], v82, s26, v[198:199]
	v_lshlrev_b64 v[90:91], 11, v[84:85]
	s_or_b64 exec, exec, s[0:1]
	v_lshl_add_u64 v[84:85], v[82:83], 0, s[38:39]
	v_lshl_add_u64 v[90:91], v[200:201], 0, v[90:91]
	v_cndmask_b32_e32 v85, v91, v85, vcc
	v_cndmask_b32_e32 v84, v90, v84, vcc
	global_load_dwordx4 v[142:145], v[82:83], off offset:16
	global_load_dwordx4 v[146:149], v[82:83], off
	global_load_dwordx4 v[110:113], v[84:85], off offset:16
	global_load_dwordx4 v[126:129], v[84:85], off
	v_min_i32_e32 v82, 0x187, v92
	v_ashrrev_i32_e32 v83, 31, v82
	v_lshl_add_u64 v[82:83], v[82:83], 2, s[40:41]
	global_load_dword v232, v[82:83], off
	v_mov_b32_e32 v82, v15
	v_mov_b32_e32 v15, v17
	v_mov_b32_e32 v83, v16
	v_pk_mul_f32 v[14:15], v[212:213], v[14:15]
	v_pk_mul_f32 v[12:13], v[204:205], v[12:13]
	v_pk_mul_f32 v[10:11], v[202:203], v[10:11]
	v_pk_fma_f32 v[14:15], v[210:211], v[82:83], v[14:15]
	v_mov_b32_e32 v16, v12
	v_mov_b32_e32 v17, v10
	v_mov_b32_e32 v10, v13
	v_pk_add_f32 v[10:11], v[16:17], v[10:11]
	v_add_f32_e32 v12, v14, v15
	v_add_f32_e32 v11, v11, v12
	v_add_f32_e32 v10, v10, v11
	v_mov_b32_e32 v11, v24
	v_pk_mul_f32 v[14:15], v[202:203], v[18:19]
	v_add_f32_dpp v10, v10, v10 quad_perm:[1,0,3,2] row_mask:0xf bank_mask:0xf bound_ctrl:1
	v_mov_b32_e32 v17, v14
	v_subrev_u32_e32 v18, 24, v223
	v_min_i32_e32 v255, 0x187, v18
	v_lshl_add_u32 v255, v255, 2, s101
	ds_read_b32 v18, v255
	s_waitcnt lgkmcnt(0)
	v_add_f32_dpp v236, v10, v10 quad_perm:[2,3,0,1] row_mask:0xf bank_mask:0xf bound_ctrl:1
	v_mov_b32_e32 v10, v23
	v_mov_b32_e32 v23, v25
	v_pk_mul_f32 v[12:13], v[212:213], v[22:23]
	v_cmp_lt_i32_e32 vcc, s19, v18
	v_pk_fma_f32 v[10:11], v[210:211], v[10:11], v[12:13]
	v_pk_mul_f32 v[12:13], v[204:205], v[20:21]
	v_add_f32_e32 v10, v10, v11
	v_mov_b32_e32 v16, v12
	v_mov_b32_e32 v14, v13
	v_pk_add_f32 v[12:13], v[16:17], v[14:15]
	v_mov_b32_e32 v11, v32
	v_add_f32_e32 v10, v13, v10
	v_add_f32_e32 v10, v12, v10
	v_pk_mul_f32 v[14:15], v[202:203], v[26:27]
	v_mov_b32_e32 v237, 0
	v_add_f32_dpp v10, v10, v10 quad_perm:[1,0,3,2] row_mask:0xf bank_mask:0xf bound_ctrl:1
	v_mov_b32_e32 v17, v14
	v_mov_b32_e32 v239, 0
	v_add_f32_dpp v238, v10, v10 quad_perm:[2,3,0,1] row_mask:0xf bank_mask:0xf bound_ctrl:1
	v_mov_b32_e32 v10, v31
	v_mov_b32_e32 v31, v33
	v_pk_mul_f32 v[12:13], v[212:213], v[30:31]
	v_mov_b32_e32 v241, 0
	v_pk_fma_f32 v[10:11], v[210:211], v[10:11], v[12:13]
	v_pk_mul_f32 v[12:13], v[204:205], v[28:29]
	v_add_f32_e32 v10, v10, v11
	v_mov_b32_e32 v16, v12
	v_mov_b32_e32 v14, v13
	v_pk_add_f32 v[12:13], v[16:17], v[14:15]
	s_waitcnt vmcnt(23)
	v_mov_b32_e32 v11, v76
	v_add_f32_e32 v10, v13, v10
	v_add_f32_e32 v10, v12, v10
	v_pk_mul_f32 v[14:15], v[202:203], v[70:71]
	v_mov_b32_dpp v237, v236 row_half_mirror row_mask:0xf bank_mask:0xf
	v_add_f32_dpp v10, v10, v10 quad_perm:[1,0,3,2] row_mask:0xf bank_mask:0xf bound_ctrl:1
	v_mov_b32_e32 v17, v14
	v_mov_b32_dpp v239, v238 row_half_mirror row_mask:0xf bank_mask:0xf
	v_add_f32_dpp v240, v10, v10 quad_perm:[2,3,0,1] row_mask:0xf bank_mask:0xf bound_ctrl:1
	v_mov_b32_e32 v10, v75
	v_mov_b32_e32 v75, v77
	v_pk_mul_f32 v[12:13], v[212:213], v[74:75]
	v_mov_b32_e32 v77, 0
	v_pk_fma_f32 v[10:11], v[210:211], v[10:11], v[12:13]
	v_pk_mul_f32 v[12:13], v[204:205], v[72:73]
	v_add_f32_e32 v10, v10, v11
	v_mov_b32_e32 v16, v12
	v_mov_b32_e32 v14, v13
	v_pk_add_f32 v[12:13], v[16:17], v[14:15]
	v_cndmask_b32_e64 v11, 0, 1, vcc
	v_add_f32_e32 v10, v13, v10
	v_add_f32_e32 v10, v12, v10
	v_cmp_gt_i32_e32 vcc, s24, v18
	v_mov_b32_dpp v241, v240 row_half_mirror row_mask:0xf bank_mask:0xf
	v_add_f32_dpp v10, v10, v10 quad_perm:[1,0,3,2] row_mask:0xf bank_mask:0xf bound_ctrl:1
	v_cndmask_b32_e32 v11, 2, v11, vcc
	v_mul_i32_i24_e32 v12, 0xffffff7f, v11
	v_add_f32_dpp v76, v10, v10 quad_perm:[2,3,0,1] row_mask:0xf bank_mask:0xf bound_ctrl:1
	v_min_i32_e32 v10, 0x182, v18
	v_lshlrev_b32_e32 v11, 1, v11
	v_add_lshl_u32 v10, v12, v10, v11
	v_sub_u32_e32 v156, s18, v10
	v_mov_b32_dpp v77, v76 row_half_mirror row_mask:0xf bank_mask:0xf
	v_cmp_lt_i32_e32 vcc, s25, v156
	v_cmp_gt_i32_e64 s[0:1], s17, v156
	s_and_saveexec_b64 s[14:15], s[0:1]
	s_xor_b64 s[0:1], exec, s[14:15]
	v_ashrrev_i32_e32 v11, 31, v156
	v_mov_b32_e32 v10, v156
	v_lshlrev_b64 v[10:11], 11, v[10:11]
	v_lshl_add_u64 v[14:15], v[194:195], 0, v[10:11]
	s_andn2_saveexec_b64 s[0:1], s[0:1]
	v_add_u32_e32 v10, 0xfffff800, v156
	v_mad_u64_u32 v[14:15], s[14:15], v10, s26, v[198:199]
	v_lshlrev_b64 v[10:11], 11, v[156:157]
	s_or_b64 exec, exec, s[0:1]
	v_lshl_add_u64 v[12:13], v[14:15], 0, s[38:39]
	v_lshl_add_u64 v[10:11], v[200:201], 0, v[10:11]
	v_min_i32_e32 v18, 0x187, v18
	v_cndmask_b32_e32 v21, v11, v13, vcc
	v_cndmask_b32_e32 v20, v10, v12, vcc
	global_load_dwordx4 v[10:13], v[14:15], off offset:16
	s_nop 0
	global_load_dwordx4 v[14:17], v[14:15], off
	s_nop 0
	global_load_dwordx4 v[90:93], v[20:21], off offset:16
	global_load_dwordx4 v[150:153], v[20:21], off
	v_ashrrev_i32_e32 v19, 31, v18
	v_lshl_add_u64 v[18:19], v[18:19], 2, s[40:41]
	global_load_dword v233, v[18:19], off
	v_add_u32_e32 v26, -16, v223
	v_min_i32_e32 v255, 0x187, v26
	v_lshl_add_u32 v255, v255, 2, s101
	ds_read_b32 v26, v255
	s_waitcnt lgkmcnt(0)
	v_cmp_lt_i32_e32 vcc, s19, v26
	v_min_i32_e32 v18, 0x182, v26
	s_nop 0
	v_cndmask_b32_e64 v19, 0, 1, vcc
	v_cmp_gt_i32_e32 vcc, s24, v26
	s_nop 1
	v_cndmask_b32_e32 v19, 2, v19, vcc
	v_mul_i32_i24_e32 v20, 0xffffff7f, v19
	v_lshlrev_b32_e32 v19, 1, v19
	v_add_lshl_u32 v18, v20, v18, v19
	v_sub_u32_e32 v18, s18, v18
	v_cmp_lt_i32_e32 vcc, s25, v18
	v_cmp_gt_i32_e64 s[0:1], s17, v18
	s_and_saveexec_b64 s[14:15], s[0:1]
	s_xor_b64 s[0:1], exec, s[14:15]
	v_ashrrev_i32_e32 v19, 31, v18
	v_lshlrev_b64 v[20:21], 11, v[18:19]
	v_lshl_add_u64 v[22:23], v[194:195], 0, v[20:21]
	s_andn2_saveexec_b64 s[0:1], s[0:1]
	v_add_u32_e32 v19, 0xfffff800, v18
	v_mad_u64_u32 v[22:23], s[14:15], v19, s26, v[198:199]
	v_mov_b32_e32 v19, v157
	v_lshlrev_b64 v[20:21], 11, v[18:19]
	s_or_b64 exec, exec, s[0:1]
	v_lshl_add_u64 v[18:19], v[22:23], 0, s[38:39]
	v_lshl_add_u64 v[20:21], v[200:201], 0, v[20:21]
	v_min_i32_e32 v26, 0x187, v26
	v_cndmask_b32_e32 v29, v21, v19, vcc
	v_cndmask_b32_e32 v28, v20, v18, vcc
	global_load_dwordx4 v[18:21], v[22:23], off offset:16
	s_nop 0
	global_load_dwordx4 v[22:25], v[22:23], off
	s_nop 0
	global_load_dwordx4 v[82:85], v[28:29], off offset:16
	global_load_dwordx4 v[98:101], v[28:29], off
	v_ashrrev_i32_e32 v27, 31, v26
	v_lshl_add_u64 v[26:27], v[26:27], 2, s[40:41]
	global_load_dword v234, v[26:27], off
	v_add_u32_e32 v70, -8, v223
	v_min_i32_e32 v255, 0x187, v70
	v_lshl_add_u32 v255, v255, 2, s101
	ds_read_b32 v70, v255
	s_waitcnt lgkmcnt(0)
	v_cmp_lt_i32_e32 vcc, s19, v70
	v_min_i32_e32 v26, 0x182, v70
	s_nop 0
	v_cndmask_b32_e64 v27, 0, 1, vcc
	v_cmp_gt_i32_e32 vcc, s24, v70
	s_nop 1
	v_cndmask_b32_e32 v27, 2, v27, vcc
	v_mul_i32_i24_e32 v28, 0xffffff7f, v27
	v_lshlrev_b32_e32 v27, 1, v27
	v_add_lshl_u32 v26, v28, v26, v27
	v_sub_u32_e32 v26, s18, v26
	v_cmp_lt_i32_e32 vcc, s25, v26
	v_cmp_gt_i32_e64 s[0:1], s17, v26
	s_and_saveexec_b64 s[14:15], s[0:1]
	s_xor_b64 s[0:1], exec, s[14:15]
	v_ashrrev_i32_e32 v27, 31, v26
	v_lshlrev_b64 v[28:29], 11, v[26:27]
	v_lshl_add_u64 v[30:31], v[194:195], 0, v[28:29]
	s_andn2_saveexec_b64 s[0:1], s[0:1]
	v_add_u32_e32 v27, 0xfffff800, v26
	v_mad_u64_u32 v[30:31], s[14:15], v27, s26, v[198:199]
	v_mov_b32_e32 v27, v157
	v_lshlrev_b64 v[28:29], 11, v[26:27]
	s_or_b64 exec, exec, s[0:1]
	v_lshl_add_u64 v[26:27], v[30:31], 0, s[38:39]
	v_lshl_add_u64 v[28:29], v[200:201], 0, v[28:29]
	v_min_i32_e32 v70, 0x187, v70
	v_cndmask_b32_e32 v73, v29, v27, vcc
	v_cndmask_b32_e32 v72, v28, v26, vcc
	global_load_dwordx4 v[26:29], v[30:31], off offset:16
	s_nop 0
	global_load_dwordx4 v[30:33], v[30:31], off
	s_nop 0
	global_load_dwordx4 v[106:109], v[72:73], off offset:16
	global_load_dwordx4 v[130:133], v[72:73], off
	v_ashrrev_i32_e32 v71, 31, v70
	v_lshl_add_u64 v[70:71], v[70:71], 2, s[40:41]
	global_load_dword v235, v[70:71], off
	v_min_i32_e32 v255, 0x187, v223
	v_lshl_add_u32 v255, v255, 2, s101
	ds_read_b32 v254, v255
	s_waitcnt lgkmcnt(0)
	v_cmp_lt_i32_e32 vcc, s19, v254
	v_min_i32_e32 v70, 0x182, v254
	s_nop 0
	v_cndmask_b32_e64 v71, 0, 1, vcc
	v_cmp_gt_i32_e32 vcc, s24, v254
	s_nop 1
	v_cndmask_b32_e32 v71, 2, v71, vcc
	v_mul_i32_i24_e32 v72, 0xffffff7f, v71
	v_lshlrev_b32_e32 v71, 1, v71
	v_add_lshl_u32 v70, v72, v70, v71
	v_sub_u32_e32 v72, s18, v70
	v_cmp_lt_i32_e32 vcc, s25, v72
	v_cmp_gt_i32_e64 s[0:1], s17, v72
	s_and_saveexec_b64 s[14:15], s[0:1]
	s_xor_b64 s[0:1], exec, s[14:15]
	v_ashrrev_i32_e32 v73, 31, v72
	v_lshlrev_b64 v[70:71], 11, v[72:73]
	v_lshl_add_u64 v[74:75], v[194:195], 0, v[70:71]
	s_andn2_saveexec_b64 s[0:1], s[0:1]
	v_add_u32_e32 v70, 0xfffff800, v72
	v_mov_b32_e32 v73, v157
	v_mad_u64_u32 v[74:75], s[14:15], v70, s26, v[198:199]
	v_lshlrev_b64 v[70:71], 11, v[72:73]
	s_or_b64 exec, exec, s[0:1]
	v_add_f32_e32 v72, v236, v237
	v_add_f32_e32 v73, v228, v72
	v_max_f32_e32 v72, v225, v225
	v_max_f32_e32 v156, v72, v73
	v_sub_f32_e32 v73, v73, v156
	v_mul_f32_e32 v73, 0x3fb8aa3b, v73
	v_exp_f32_e32 v228, v73
	v_add_f32_e32 v73, v238, v239
	v_add_f32_e32 v73, v227, v73
	v_sub_f32_e32 v72, v225, v156
	v_max_f32_e32 v225, v156, v73
	v_sub_f32_e32 v73, v73, v225
	v_mul_f32_e32 v73, 0x3fb8aa3b, v73
	v_sub_f32_e32 v156, v156, v225
	v_exp_f32_e32 v238, v73
	v_add_f32_e32 v73, v240, v241
	v_mul_f32_e32 v156, 0x3fb8aa3b, v156
	v_add_f32_e32 v73, v226, v73
	v_mul_f32_e32 v72, 0x3fb8aa3b, v72
	v_exp_f32_e32 v236, v156
	v_max_f32_e32 v156, v225, v73
	v_exp_f32_e32 v72, v72
	v_sub_f32_e32 v225, v225, v156
	v_sub_f32_e32 v73, v73, v156
	v_mul_f32_e32 v225, 0x3fb8aa3b, v225
	v_mul_f32_e32 v73, 0x3fb8aa3b, v73
	v_exp_f32_e32 v226, v225
	v_exp_f32_e32 v240, v73
	v_fma_f32 v73, v224, v72, v228
	v_fma_f32 v73, v73, v236, v238
	s_waitcnt vmcnt(30)
	v_pk_mul_f32 v[42:43], v[42:43], v[228:229] op_sel_hi:[1,0]
	v_fma_f32 v225, v73, v226, v240
	v_add_f32_e32 v73, v76, v77
	v_add_f32_e32 v73, v222, v73
	v_max_f32_e32 v227, v156, v73
	v_sub_f32_e32 v73, v73, v227
	v_sub_f32_e32 v76, v156, v227
	v_mul_f32_e32 v73, 0x3fb8aa3b, v73
	v_mul_f32_e32 v76, 0x3fb8aa3b, v76
	v_exp_f32_e32 v156, v73
	v_exp_f32_e32 v224, v76
	v_pk_fma_f32 v[42:43], v[220:221], v[72:73], v[42:43] op_sel_hi:[1,0,1]
	v_pk_mul_f32 v[50:51], v[50:51], v[238:239] op_sel_hi:[1,0]
	v_pk_mul_f32 v[6:7], v[6:7], v[156:157] op_sel_hi:[1,0]
	v_pk_fma_f32 v[42:43], v[42:43], v[236:237], v[50:51] op_sel_hi:[1,0,1]
	v_pk_mul_f32 v[50:51], v[58:59], v[240:241] op_sel_hi:[1,0]
	v_pk_mul_f32 v[8:9], v[8:9], v[156:157] op_sel_hi:[1,0]
	v_pk_fma_f32 v[42:43], v[42:43], v[226:227], v[50:51] op_sel_hi:[1,0,1]
	v_pk_mul_f32 v[2:3], v[2:3], v[156:157] op_sel_hi:[1,0]
	v_pk_fma_f32 v[42:43], v[42:43], v[224:225], v[6:7] op_sel_hi:[1,0,1]
	v_pk_mul_f32 v[6:7], v[44:45], v[228:229] op_sel_hi:[1,0]
	v_pk_mul_f32 v[44:45], v[52:53], v[238:239] op_sel_hi:[1,0]
	v_pk_fma_f32 v[6:7], v[218:219], v[72:73], v[6:7] op_sel_hi:[1,0,1]
	v_pk_mul_f32 v[4:5], v[4:5], v[156:157] op_sel_hi:[1,0]
	v_pk_fma_f32 v[6:7], v[6:7], v[236:237], v[44:45] op_sel_hi:[1,0,1]
	v_pk_mul_f32 v[44:45], v[60:61], v[240:241] op_sel_hi:[1,0]
	v_fmac_f32_e32 v156, v225, v224
	v_pk_fma_f32 v[6:7], v[6:7], v[226:227], v[44:45] op_sel_hi:[1,0,1]
	s_add_i32 s3, s3, 8
	v_pk_fma_f32 v[44:45], v[6:7], v[224:225], v[8:9] op_sel_hi:[1,0,1]
	v_pk_mul_f32 v[6:7], v[34:35], v[228:229] op_sel_hi:[1,0]
	v_pk_mul_f32 v[8:9], v[38:39], v[238:239] op_sel_hi:[1,0]
	v_pk_fma_f32 v[6:7], v[214:215], v[72:73], v[6:7] op_sel_hi:[1,0,1]
	v_min_i32_e32 v38, 0x187, v254
	v_pk_fma_f32 v[6:7], v[6:7], v[236:237], v[8:9] op_sel_hi:[1,0,1]
	v_pk_mul_f32 v[8:9], v[46:47], v[240:241] op_sel_hi:[1,0]
	v_ashrrev_i32_e32 v39, 31, v38
	v_pk_fma_f32 v[6:7], v[6:7], v[226:227], v[8:9] op_sel_hi:[1,0,1]
	v_lshl_add_u64 v[38:39], v[38:39], 2, s[40:41]
	v_pk_fma_f32 v[34:35], v[6:7], v[224:225], v[2:3] op_sel_hi:[1,0,1]
	v_pk_mul_f32 v[2:3], v[36:37], v[228:229] op_sel_hi:[1,0]
	v_pk_mul_f32 v[6:7], v[40:41], v[238:239] op_sel_hi:[1,0]
	v_pk_fma_f32 v[2:3], v[216:217], v[72:73], v[2:3] op_sel_hi:[1,0,1]
	v_pk_mul_f32 v[40:41], v[206:207], v[114:115]
	v_pk_fma_f32 v[2:3], v[2:3], v[236:237], v[6:7] op_sel_hi:[1,0,1]
	v_pk_mul_f32 v[6:7], v[48:49], v[240:241] op_sel_hi:[1,0]
	s_cmp_gt_u32 s3, 39
	v_pk_fma_f32 v[2:3], v[2:3], v[226:227], v[6:7] op_sel_hi:[1,0,1]
	v_add_u32_e32 v223, 64, v223
	v_pk_fma_f32 v[36:37], v[2:3], v[224:225], v[4:5] op_sel_hi:[1,0,1]
	v_lshl_add_u64 v[2:3], v[74:75], 0, s[38:39]
	v_lshl_add_u64 v[4:5], v[200:201], 0, v[70:71]
	v_cndmask_b32_e32 v7, v5, v3, vcc
	v_cndmask_b32_e32 v6, v4, v2, vcc
	global_load_dwordx4 v[70:73], v[74:75], off offset:16
	s_nop 0
	global_load_dwordx4 v[74:77], v[74:75], off
	s_nop 0
	global_load_dwordx4 v[2:5], v[6:7], off offset:16
	s_nop 0
	global_load_dwordx4 v[6:9], v[6:7], off
	s_nop 0
	global_load_dword v222, v[38:39], off
	v_pk_mul_f32 v[38:39], v[208:209], v[116:117]
	s_nop 0
	v_pk_mov_b32 v[46:47], v[40:41], v[38:39] op_sel:[1,0]
	v_mov_b32_e32 v41, v39
	v_pk_add_f32 v[38:39], v[46:47], v[40:41]
	v_pk_mul_f32 v[40:41], v[204:205], v[104:105]
	v_pk_mul_f32 v[46:47], v[202:203], v[102:103]
	v_mov_b32_e32 v48, v40
	v_mov_b32_e32 v49, v46
	v_mov_b32_e32 v46, v41
	v_pk_add_f32 v[40:41], v[48:49], v[46:47]
	v_add_f32_e32 v38, v38, v39
	v_add_f32_e32 v38, v38, v41
	v_add_f32_e32 v38, v40, v38
	s_waitcnt vmcnt(33)
	v_pk_mul_f32 v[46:47], v[208:209], v[124:125]
	v_pk_mul_f32 v[48:49], v[206:207], v[122:123]
	v_add_f32_dpp v38, v38, v38 quad_perm:[1,0,3,2] row_mask:0xf bank_mask:0xf bound_ctrl:1
	v_pk_mov_b32 v[50:51], v[48:49], v[46:47] op_sel:[1,0]
	v_mov_b32_e32 v49, v47
	v_add_f32_dpp v38, v38, v38 quad_perm:[2,3,0,1] row_mask:0xf bank_mask:0xf bound_ctrl:1
	v_pk_add_f32 v[46:47], v[50:51], v[48:49]
	v_pk_mul_f32 v[48:49], v[204:205], v[120:121]
	v_add_f32_dpp v38, v38, v38 row_half_mirror row_mask:0xf bank_mask:0xf bound_ctrl:1
	v_add_f32_e32 v39, v229, v38
	v_max_f32_e32 v41, v227, v39
	v_sub_f32_e32 v39, v39, v41
	v_pk_mul_f32 v[50:51], v[202:203], v[118:119]
	v_mul_f32_e32 v39, 0x3fb8aa3b, v39
	v_mov_b32_e32 v52, v48
	v_mov_b32_e32 v53, v50
	v_mov_b32_e32 v50, v49
	v_exp_f32_e32 v40, v39
	v_pk_add_f32 v[48:49], v[52:53], v[50:51]
	v_add_f32_e32 v39, v46, v47
	v_add_f32_e32 v39, v39, v49
	v_add_f32_e32 v39, v48, v39
	s_waitcnt vmcnt(28)
	v_pk_mul_f32 v[50:51], v[208:209], v[140:141]
	v_pk_mul_f32 v[52:53], v[206:207], v[138:139]
	v_add_f32_dpp v39, v39, v39 quad_perm:[1,0,3,2] row_mask:0xf bank_mask:0xf bound_ctrl:1
	v_pk_mov_b32 v[58:59], v[52:53], v[50:51] op_sel:[1,0]
	v_mov_b32_e32 v53, v51
	v_add_f32_dpp v39, v39, v39 quad_perm:[2,3,0,1] row_mask:0xf bank_mask:0xf bound_ctrl:1
	v_pk_add_f32 v[50:51], v[58:59], v[52:53]
	v_pk_mul_f32 v[52:53], v[204:205], v[136:137]
	v_add_f32_dpp v39, v39, v39 row_half_mirror row_mask:0xf bank_mask:0xf bound_ctrl:1
	v_add_f32_e32 v39, v230, v39
	v_max_f32_e32 v47, v41, v39
	v_sub_f32_e32 v39, v39, v47
	v_pk_mul_f32 v[58:59], v[202:203], v[134:135]
	v_mul_f32_e32 v39, 0x3fb8aa3b, v39
	v_mov_b32_e32 v60, v52
	v_mov_b32_e32 v61, v58
	v_mov_b32_e32 v58, v53
	v_exp_f32_e32 v48, v39
	v_pk_add_f32 v[52:53], v[60:61], v[58:59]
	v_add_f32_e32 v39, v50, v51
	v_add_f32_e32 v39, v39, v53
	v_add_f32_e32 v39, v52, v39
	v_sub_f32_e32 v38, v227, v41
	v_sub_f32_e32 v41, v41, v47
	v_add_f32_dpp v39, v39, v39 quad_perm:[1,0,3,2] row_mask:0xf bank_mask:0xf bound_ctrl:1
	v_mul_f32_e32 v41, 0x3fb8aa3b, v41
	s_waitcnt vmcnt(23)
; __device__ __forceinline__ void p_attn_sample(const float* P, const float* ck, const float* cv, const float* relb, bf16* heads, const float* sbt, unsigned* qctr, volatile LAS unsigned* slot, int wave, int lane_in) {
;     ...
;         SLOADB(ak0, ak1, av0, av1, ab, 0)
; #pragma unroll 1
;         for (int it0 = 0; it0 < 48; it0 += 8) {
;             SLOADB(bk0, bk1, bv0, bv1, bbv, it0 + 4)
;             SPROCB(ak0, ak1, av0, av1, ab)
;             SLOADB(ak0, ak1, av0, av1, ab, it0 + 8)
;             SPROCB(bk0, bk1, bv0, bv1, bbv)
;         }
	v_pk_mul_f32 v[58:59], v[208:209], v[148:149]
	v_add_f32_dpp v39, v39, v39 quad_perm:[2,3,0,1] row_mask:0xf bank_mask:0xf bound_ctrl:1
	v_pk_mul_f32 v[60:61], v[206:207], v[146:147]
	v_exp_f32_e32 v46, v41
	v_add_f32_dpp v39, v39, v39 row_half_mirror row_mask:0xf bank_mask:0xf bound_ctrl:1
	v_add_f32_e32 v39, v231, v39
	v_max_f32_e32 v41, v47, v39
	v_pk_mov_b32 v[102:103], v[60:61], v[58:59] op_sel:[1,0]
	v_mov_b32_e32 v61, v59
	v_sub_f32_e32 v39, v39, v41
	v_pk_add_f32 v[58:59], v[102:103], v[60:61]
	v_pk_mul_f32 v[60:61], v[204:205], v[144:145]
	v_pk_mul_f32 v[102:103], v[202:203], v[142:143]
	v_mul_f32_e32 v39, 0x3fb8aa3b, v39
	v_mov_b32_e32 v104, v60
	v_mov_b32_e32 v105, v102
	v_mov_b32_e32 v102, v61
	v_exp_f32_e32 v52, v39
	v_pk_add_f32 v[60:61], v[104:105], v[102:103]
	v_add_f32_e32 v39, v58, v59
	v_add_f32_e32 v39, v39, v61
	v_add_f32_e32 v39, v60, v39
	v_mul_f32_e32 v38, 0x3fb8aa3b, v38
	v_exp_f32_e32 v38, v38
	v_add_f32_dpp v39, v39, v39 quad_perm:[1,0,3,2] row_mask:0xf bank_mask:0xf bound_ctrl:1
	v_sub_f32_e32 v47, v47, v41
	v_mul_f32_e32 v47, 0x3fb8aa3b, v47
	v_add_f32_dpp v39, v39, v39 quad_perm:[2,3,0,1] row_mask:0xf bank_mask:0xf bound_ctrl:1
	v_exp_f32_e32 v50, v47
	s_nop 0
	v_add_f32_dpp v39, v39, v39 row_half_mirror row_mask:0xf bank_mask:0xf bound_ctrl:1
	s_waitcnt vmcnt(20)
	v_add_f32_e32 v39, v232, v39
	v_max_f32_e32 v225, v41, v39
	v_sub_f32_e32 v39, v39, v225
	v_mul_f32_e32 v39, 0x3fb8aa3b, v39
	v_sub_f32_e32 v41, v41, v225
	v_exp_f32_e32 v60, v39
	v_fma_f32 v39, v156, v38, v40
	v_mul_f32_e32 v41, 0x3fb8aa3b, v41
	v_fma_f32 v39, v39, v46, v48
	v_exp_f32_e32 v58, v41
	v_fma_f32 v39, v39, v50, v52
	v_pk_mul_f32 v[62:63], v[62:63], v[40:41] op_sel_hi:[1,0]
	v_fma_f32 v224, v39, v58, v60
	v_pk_fma_f32 v[42:43], v[42:43], v[38:39], v[62:63] op_sel_hi:[1,0,1]
	v_pk_mul_f32 v[62:63], v[78:79], v[48:49] op_sel_hi:[1,0]
	s_nop 0
	v_pk_fma_f32 v[42:43], v[42:43], v[46:47], v[62:63] op_sel_hi:[1,0,1]
	v_pk_mul_f32 v[62:63], v[94:95], v[52:53] op_sel_hi:[1,0]
	s_nop 0
	v_pk_fma_f32 v[42:43], v[42:43], v[50:51], v[62:63] op_sel_hi:[1,0,1]
	v_pk_mul_f32 v[62:63], v[126:127], v[60:61] op_sel_hi:[1,0]
	s_nop 0
	v_pk_fma_f32 v[220:221], v[42:43], v[58:59], v[62:63] op_sel_hi:[1,0,1]
	v_pk_mul_f32 v[42:43], v[64:65], v[40:41] op_sel_hi:[1,0]
	s_nop 0
	v_pk_fma_f32 v[42:43], v[44:45], v[38:39], v[42:43] op_sel_hi:[1,0,1]
	v_pk_mul_f32 v[44:45], v[80:81], v[48:49] op_sel_hi:[1,0]
	s_nop 0
	v_pk_fma_f32 v[42:43], v[42:43], v[46:47], v[44:45] op_sel_hi:[1,0,1]
	v_pk_mul_f32 v[44:45], v[96:97], v[52:53] op_sel_hi:[1,0]
	s_nop 0
	v_pk_fma_f32 v[42:43], v[42:43], v[50:51], v[44:45] op_sel_hi:[1,0,1]
	v_pk_mul_f32 v[44:45], v[128:129], v[60:61] op_sel_hi:[1,0]
	s_nop 0
	v_pk_fma_f32 v[218:219], v[42:43], v[58:59], v[44:45] op_sel_hi:[1,0,1]
	v_pk_mul_f32 v[42:43], v[54:55], v[40:41] op_sel_hi:[1,0]
	s_nop 0
	v_pk_fma_f32 v[34:35], v[34:35], v[38:39], v[42:43] op_sel_hi:[1,0,1]
	v_pk_mul_f32 v[42:43], v[66:67], v[48:49] op_sel_hi:[1,0]
	s_nop 0
	v_pk_fma_f32 v[34:35], v[34:35], v[46:47], v[42:43] op_sel_hi:[1,0,1]
	v_pk_mul_f32 v[42:43], v[86:87], v[52:53] op_sel_hi:[1,0]
	s_nop 0
	v_pk_fma_f32 v[34:35], v[34:35], v[50:51], v[42:43] op_sel_hi:[1,0,1]
	v_pk_mul_f32 v[42:43], v[110:111], v[60:61] op_sel_hi:[1,0]
	s_nop 0
	v_pk_fma_f32 v[214:215], v[34:35], v[58:59], v[42:43] op_sel_hi:[1,0,1]
	v_pk_mul_f32 v[34:35], v[56:57], v[40:41] op_sel_hi:[1,0]
	s_nop 0
	v_pk_fma_f32 v[34:35], v[36:37], v[38:39], v[34:35] op_sel_hi:[1,0,1]
	v_pk_mul_f32 v[36:37], v[68:69], v[48:49] op_sel_hi:[1,0]
	s_nop 0
	v_pk_fma_f32 v[34:35], v[34:35], v[46:47], v[36:37] op_sel_hi:[1,0,1]
	v_pk_mul_f32 v[36:37], v[88:89], v[52:53] op_sel_hi:[1,0]
	s_nop 0
	v_pk_fma_f32 v[34:35], v[34:35], v[50:51], v[36:37] op_sel_hi:[1,0,1]
	v_pk_mul_f32 v[36:37], v[112:113], v[60:61] op_sel_hi:[1,0]
	s_nop 0
	v_pk_fma_f32 v[216:217], v[34:35], v[58:59], v[36:37] op_sel_hi:[1,0,1]
	s_cbranch_scc1 .LBB0_1285
	s_waitcnt vmcnt(17)
	v_mov_b64_e32 v[34:35], v[90:91]
	s_waitcnt vmcnt(12)
	v_mov_b64_e32 v[38:39], v[82:83]
	s_waitcnt vmcnt(7)
	v_mov_b64_e32 v[46:47], v[106:107]
	v_mov_b64_e32 v[42:43], v[150:151]
	v_mov_b64_e32 v[50:51], v[98:99]
	s_waitcnt vmcnt(6)
	v_mov_b64_e32 v[58:59], v[130:131]
	v_mov_b64_e32 v[36:37], v[92:93]
	v_mov_b64_e32 v[40:41], v[84:85]
	v_mov_b64_e32 v[48:49], v[108:109]
	v_mov_b64_e32 v[44:45], v[152:153]
	v_mov_b64_e32 v[52:53], v[100:101]
	v_mov_b64_e32 v[60:61], v[132:133]
	s_waitcnt vmcnt(5)
	v_mov_b32_e32 v226, v235
	v_mov_b32_e32 v227, v234
	v_mov_b32_e32 v228, v233
	s_branch .LBB0_1251

.LBB0_1383:
	v_subrev_u32_e32 v66, 56, v222
	v_min_i32_e32 v255, 0x187, v66
	v_lshl_add_u32 v255, v255, 2, s101
	ds_read_b32 v66, v255
	s_waitcnt lgkmcnt(0)
	v_cmp_lt_i32_e32 vcc, s19, v66
	v_min_i32_e32 v54, 0x182, v66
	s_nop 0
	v_cndmask_b32_e64 v55, 0, 1, vcc
	v_cmp_gt_i32_e32 vcc, s23, v66
	s_nop 1
	v_cndmask_b32_e32 v55, 2, v55, vcc
	v_mul_i32_i24_e32 v56, 0xffffff7f, v55
	v_lshlrev_b32_e32 v55, 1, v55
	v_add_lshl_u32 v54, v56, v54, v55
	v_sub_u32_e32 v156, s18, v54
	v_cmp_lt_i32_e32 vcc, s26, v156
	v_cmp_gt_i32_e64 s[0:1], s17, v156
	s_and_saveexec_b64 s[14:15], s[0:1]
	s_xor_b64 s[0:1], exec, s[14:15]
	v_ashrrev_i32_e32 v55, 31, v156
	v_mov_b32_e32 v54, v156
	v_lshlrev_b64 v[56:57], 11, v[54:55]
	v_lshl_add_u64 v[54:55], v[194:195], 0, v[56:57]
	s_andn2_saveexec_b64 s[0:1], s[0:1]
	v_add_u32_e32 v54, 0xfffff800, v156
	v_mad_u64_u32 v[54:55], s[14:15], v54, s27, v[196:197]
	v_lshlrev_b64 v[56:57], 11, v[156:157]
	s_or_b64 exec, exec, s[0:1]
	v_lshl_add_u64 v[62:63], v[54:55], 0, s[28:29]
	v_lshl_add_u64 v[56:57], v[198:199], 0, v[56:57]
	v_cndmask_b32_e32 v63, v57, v63, vcc
	v_cndmask_b32_e32 v62, v56, v62, vcc
	v_min_i32_e32 v66, 0x187, v66
	global_load_dwordx4 v[102:105], v[54:55], off offset:16
	global_load_dwordx4 v[114:117], v[54:55], off
	s_nop 0
	global_load_dwordx4 v[54:57], v[62:63], off offset:16
	s_nop 0
	global_load_dwordx4 v[62:65], v[62:63], off
	v_ashrrev_i32_e32 v67, 31, v66
	v_lshl_add_u64 v[66:67], v[66:67], 2, s[30:31]
	global_load_dword v228, v[66:67], off
	v_subrev_u32_e32 v82, 48, v222
	v_min_i32_e32 v255, 0x187, v82
	v_lshl_add_u32 v255, v255, 2, s101
	ds_read_b32 v82, v255
	s_waitcnt lgkmcnt(0)
	v_cmp_lt_i32_e32 vcc, s19, v82
	v_min_i32_e32 v66, 0x182, v82
	s_nop 0
	v_cndmask_b32_e64 v67, 0, 1, vcc
	v_cmp_gt_i32_e32 vcc, s23, v82
	s_nop 1
	v_cndmask_b32_e32 v67, 2, v67, vcc
	v_mul_i32_i24_e32 v68, 0xffffff7f, v67
	v_lshlrev_b32_e32 v67, 1, v67
	v_add_lshl_u32 v66, v68, v66, v67
	v_sub_u32_e32 v68, s18, v66
	v_cmp_lt_i32_e32 vcc, s26, v68
	v_cmp_gt_i32_e64 s[0:1], s17, v68
	s_and_saveexec_b64 s[14:15], s[0:1]
	s_xor_b64 s[0:1], exec, s[14:15]
	v_ashrrev_i32_e32 v69, 31, v68
	v_lshlrev_b64 v[78:79], 11, v[68:69]
	v_lshl_add_u64 v[66:67], v[194:195], 0, v[78:79]
	s_andn2_saveexec_b64 s[0:1], s[0:1]
	v_add_u32_e32 v66, 0xfffff800, v68
	v_mov_b32_e32 v69, v157
	v_mad_u64_u32 v[66:67], s[14:15], v66, s27, v[196:197]
	v_lshlrev_b64 v[78:79], 11, v[68:69]
	s_or_b64 exec, exec, s[0:1]
	v_lshl_add_u64 v[68:69], v[66:67], 0, s[28:29]
	v_lshl_add_u64 v[78:79], v[198:199], 0, v[78:79]
	v_cndmask_b32_e32 v79, v79, v69, vcc
	v_cndmask_b32_e32 v78, v78, v68, vcc
	v_min_i32_e32 v82, 0x187, v82
	global_load_dwordx4 v[118:121], v[66:67], off offset:16
	global_load_dwordx4 v[122:125], v[66:67], off
	s_nop 0
	global_load_dwordx4 v[66:69], v[78:79], off offset:16
	s_nop 0
	global_load_dwordx4 v[78:81], v[78:79], off
	v_ashrrev_i32_e32 v83, 31, v82
	v_lshl_add_u64 v[82:83], v[82:83], 2, s[30:31]
	global_load_dword v229, v[82:83], off
	v_subrev_u32_e32 v90, 40, v222
	v_min_i32_e32 v255, 0x187, v90
	v_lshl_add_u32 v255, v255, 2, s101
	ds_read_b32 v90, v255
	s_waitcnt lgkmcnt(0)
	v_cmp_lt_i32_e32 vcc, s19, v90
	v_min_i32_e32 v82, 0x182, v90
	s_nop 0
	v_cndmask_b32_e64 v83, 0, 1, vcc
	v_cmp_gt_i32_e32 vcc, s23, v90
	s_nop 1
	v_cndmask_b32_e32 v83, 2, v83, vcc
	v_mul_i32_i24_e32 v84, 0xffffff7f, v83
	v_lshlrev_b32_e32 v83, 1, v83
	v_add_lshl_u32 v82, v84, v82, v83
	v_sub_u32_e32 v84, s18, v82
	v_cmp_lt_i32_e32 vcc, s26, v84
	v_cmp_gt_i32_e64 s[0:1], s17, v84
	s_and_saveexec_b64 s[14:15], s[0:1]
	s_xor_b64 s[0:1], exec, s[14:15]
	v_ashrrev_i32_e32 v85, 31, v84
	v_lshlrev_b64 v[86:87], 11, v[84:85]
	v_lshl_add_u64 v[82:83], v[194:195], 0, v[86:87]
	s_andn2_saveexec_b64 s[0:1], s[0:1]
	v_add_u32_e32 v82, 0xfffff800, v84
	v_mov_b32_e32 v85, v157
	v_mad_u64_u32 v[82:83], s[14:15], v82, s27, v[196:197]
	v_lshlrev_b64 v[86:87], 11, v[84:85]
	s_or_b64 exec, exec, s[0:1]
	v_lshl_add_u64 v[84:85], v[82:83], 0, s[28:29]
	v_lshl_add_u64 v[86:87], v[198:199], 0, v[86:87]
	v_cndmask_b32_e32 v85, v87, v85, vcc
	v_cndmask_b32_e32 v84, v86, v84, vcc
	global_load_dwordx4 v[134:137], v[82:83], off offset:16
	global_load_dwordx4 v[138:141], v[82:83], off
	global_load_dwordx4 v[86:89], v[84:85], off offset:16
	global_load_dwordx4 v[94:97], v[84:85], off
	v_min_i32_e32 v82, 0x187, v90
	v_ashrrev_i32_e32 v83, 31, v82
	v_lshl_add_u64 v[82:83], v[82:83], 2, s[30:31]
	global_load_dword v230, v[82:83], off
	v_subrev_u32_e32 v92, 32, v222
	v_min_i32_e32 v255, 0x187, v92
	v_lshl_add_u32 v255, v255, 2, s101
	ds_read_b32 v92, v255
	s_waitcnt lgkmcnt(0)
	v_cmp_lt_i32_e32 vcc, s19, v92
	v_min_i32_e32 v82, 0x182, v92
	s_nop 0
	v_cndmask_b32_e64 v83, 0, 1, vcc
	v_cmp_gt_i32_e32 vcc, s23, v92
	s_nop 1
	v_cndmask_b32_e32 v83, 2, v83, vcc
	v_mul_i32_i24_e32 v84, 0xffffff7f, v83
	v_lshlrev_b32_e32 v83, 1, v83
	v_add_lshl_u32 v82, v84, v82, v83
	v_sub_u32_e32 v84, s18, v82
	v_cmp_lt_i32_e32 vcc, s26, v84
	v_cmp_gt_i32_e64 s[0:1], s17, v84
	s_and_saveexec_b64 s[14:15], s[0:1]
	s_xor_b64 s[0:1], exec, s[14:15]
	v_ashrrev_i32_e32 v85, 31, v84
	v_lshlrev_b64 v[90:91], 11, v[84:85]
	v_lshl_add_u64 v[82:83], v[194:195], 0, v[90:91]
	s_andn2_saveexec_b64 s[0:1], s[0:1]
	v_add_u32_e32 v82, 0xfffff800, v84
	v_mov_b32_e32 v85, v157
	v_mad_u64_u32 v[82:83], s[14:15], v82, s27, v[196:197]
	v_lshlrev_b64 v[90:91], 11, v[84:85]
	s_or_b64 exec, exec, s[0:1]
	v_lshl_add_u64 v[84:85], v[82:83], 0, s[28:29]
	v_lshl_add_u64 v[90:91], v[198:199], 0, v[90:91]
	v_cndmask_b32_e32 v85, v91, v85, vcc
	v_cndmask_b32_e32 v84, v90, v84, vcc
	global_load_dwordx4 v[142:145], v[82:83], off offset:16
	global_load_dwordx4 v[146:149], v[82:83], off
	global_load_dwordx4 v[110:113], v[84:85], off offset:16
	global_load_dwordx4 v[126:129], v[84:85], off
	v_min_i32_e32 v82, 0x187, v92
	v_ashrrev_i32_e32 v83, 31, v82
	v_lshl_add_u64 v[82:83], v[82:83], 2, s[30:31]
	global_load_dword v231, v[82:83], off
	v_mov_b32_e32 v82, v15
	v_mov_b32_e32 v15, v17
	v_mov_b32_e32 v83, v16
	v_pk_mul_f32 v[14:15], v[210:211], v[14:15]
	v_pk_mul_f32 v[12:13], v[202:203], v[12:13]
	v_pk_mul_f32 v[10:11], v[200:201], v[10:11]
	v_pk_fma_f32 v[14:15], v[208:209], v[82:83], v[14:15]
	v_mov_b32_e32 v16, v12
	v_mov_b32_e32 v17, v10
	v_mov_b32_e32 v10, v13
	v_pk_add_f32 v[10:11], v[16:17], v[10:11]
	v_add_f32_e32 v12, v14, v15
	v_add_f32_e32 v11, v11, v12
	v_add_f32_e32 v10, v10, v11
	v_mov_b32_e32 v11, v24
	v_pk_mul_f32 v[14:15], v[200:201], v[18:19]
	v_add_f32_dpp v10, v10, v10 quad_perm:[1,0,3,2] row_mask:0xf bank_mask:0xf bound_ctrl:1
	v_mov_b32_e32 v17, v14
	v_subrev_u32_e32 v18, 24, v222
	v_min_i32_e32 v255, 0x187, v18
	v_lshl_add_u32 v255, v255, 2, s101
	ds_read_b32 v18, v255
	s_waitcnt lgkmcnt(0)
	v_add_f32_dpp v235, v10, v10 quad_perm:[2,3,0,1] row_mask:0xf bank_mask:0xf bound_ctrl:1
	v_mov_b32_e32 v10, v23
	v_mov_b32_e32 v23, v25
	v_pk_mul_f32 v[12:13], v[210:211], v[22:23]
	v_cmp_lt_i32_e32 vcc, s19, v18
	v_pk_fma_f32 v[10:11], v[208:209], v[10:11], v[12:13]
	v_pk_mul_f32 v[12:13], v[202:203], v[20:21]
	v_add_f32_e32 v10, v10, v11
	v_mov_b32_e32 v16, v12
	v_mov_b32_e32 v14, v13
	v_pk_add_f32 v[12:13], v[16:17], v[14:15]
	v_mov_b32_e32 v11, v32
	v_add_f32_e32 v10, v13, v10
	v_add_f32_e32 v10, v12, v10
	v_pk_mul_f32 v[14:15], v[200:201], v[26:27]
	v_mov_b32_e32 v236, 0
	v_add_f32_dpp v10, v10, v10 quad_perm:[1,0,3,2] row_mask:0xf bank_mask:0xf bound_ctrl:1
	v_mov_b32_e32 v17, v14
	v_mov_b32_e32 v238, 0
	v_add_f32_dpp v237, v10, v10 quad_perm:[2,3,0,1] row_mask:0xf bank_mask:0xf bound_ctrl:1
	v_mov_b32_e32 v10, v31
	v_mov_b32_e32 v31, v33
	v_pk_mul_f32 v[12:13], v[210:211], v[30:31]
	v_mov_b32_e32 v240, 0
	v_pk_fma_f32 v[10:11], v[208:209], v[10:11], v[12:13]
	v_pk_mul_f32 v[12:13], v[202:203], v[28:29]
	v_add_f32_e32 v10, v10, v11
	v_mov_b32_e32 v16, v12
	v_mov_b32_e32 v14, v13
	v_pk_add_f32 v[12:13], v[16:17], v[14:15]
	s_waitcnt vmcnt(23)
	v_mov_b32_e32 v11, v76
	v_add_f32_e32 v10, v13, v10
	v_add_f32_e32 v10, v12, v10
	v_pk_mul_f32 v[14:15], v[200:201], v[70:71]
	v_mov_b32_dpp v236, v235 row_half_mirror row_mask:0xf bank_mask:0xf
	v_add_f32_dpp v10, v10, v10 quad_perm:[1,0,3,2] row_mask:0xf bank_mask:0xf bound_ctrl:1
	v_mov_b32_e32 v17, v14
	v_mov_b32_dpp v238, v237 row_half_mirror row_mask:0xf bank_mask:0xf
	v_add_f32_dpp v239, v10, v10 quad_perm:[2,3,0,1] row_mask:0xf bank_mask:0xf bound_ctrl:1
	v_mov_b32_e32 v10, v75
	v_mov_b32_e32 v75, v77
	v_pk_mul_f32 v[12:13], v[210:211], v[74:75]
	v_mov_b32_e32 v77, 0
	v_pk_fma_f32 v[10:11], v[208:209], v[10:11], v[12:13]
	v_pk_mul_f32 v[12:13], v[202:203], v[72:73]
	v_add_f32_e32 v10, v10, v11
	v_mov_b32_e32 v16, v12
	v_mov_b32_e32 v14, v13
	v_pk_add_f32 v[12:13], v[16:17], v[14:15]
	v_cndmask_b32_e64 v11, 0, 1, vcc
	v_add_f32_e32 v10, v13, v10
	v_add_f32_e32 v10, v12, v10
	v_cmp_gt_i32_e32 vcc, s23, v18
	v_mov_b32_dpp v240, v239 row_half_mirror row_mask:0xf bank_mask:0xf
	v_add_f32_dpp v10, v10, v10 quad_perm:[1,0,3,2] row_mask:0xf bank_mask:0xf bound_ctrl:1
	v_cndmask_b32_e32 v11, 2, v11, vcc
	v_mul_i32_i24_e32 v12, 0xffffff7f, v11
	v_add_f32_dpp v76, v10, v10 quad_perm:[2,3,0,1] row_mask:0xf bank_mask:0xf bound_ctrl:1
	v_min_i32_e32 v10, 0x182, v18
	v_lshlrev_b32_e32 v11, 1, v11
	v_add_lshl_u32 v10, v12, v10, v11
	v_sub_u32_e32 v156, s18, v10
	v_mov_b32_dpp v77, v76 row_half_mirror row_mask:0xf bank_mask:0xf
	v_cmp_lt_i32_e32 vcc, s26, v156
	v_cmp_gt_i32_e64 s[0:1], s17, v156
	s_and_saveexec_b64 s[14:15], s[0:1]
	s_xor_b64 s[0:1], exec, s[14:15]
	v_ashrrev_i32_e32 v11, 31, v156
	v_mov_b32_e32 v10, v156
	v_lshlrev_b64 v[10:11], 11, v[10:11]
	v_lshl_add_u64 v[14:15], v[194:195], 0, v[10:11]
	s_andn2_saveexec_b64 s[0:1], s[0:1]
	v_add_u32_e32 v10, 0xfffff800, v156
	v_mad_u64_u32 v[14:15], s[14:15], v10, s27, v[196:197]
	v_lshlrev_b64 v[10:11], 11, v[156:157]
	s_or_b64 exec, exec, s[0:1]
	v_lshl_add_u64 v[12:13], v[14:15], 0, s[28:29]
	v_lshl_add_u64 v[10:11], v[198:199], 0, v[10:11]
	v_min_i32_e32 v18, 0x187, v18
	v_cndmask_b32_e32 v21, v11, v13, vcc
	v_cndmask_b32_e32 v20, v10, v12, vcc
	global_load_dwordx4 v[10:13], v[14:15], off offset:16
	s_nop 0
	global_load_dwordx4 v[14:17], v[14:15], off
	s_nop 0
	global_load_dwordx4 v[90:93], v[20:21], off offset:16
	global_load_dwordx4 v[150:153], v[20:21], off
	v_ashrrev_i32_e32 v19, 31, v18
	v_lshl_add_u64 v[18:19], v[18:19], 2, s[30:31]
	global_load_dword v232, v[18:19], off
	v_add_u32_e32 v26, -16, v222
	v_min_i32_e32 v255, 0x187, v26
	v_lshl_add_u32 v255, v255, 2, s101
	ds_read_b32 v26, v255
	s_waitcnt lgkmcnt(0)
	v_cmp_lt_i32_e32 vcc, s19, v26
	v_min_i32_e32 v18, 0x182, v26
	s_nop 0
	v_cndmask_b32_e64 v19, 0, 1, vcc
	v_cmp_gt_i32_e32 vcc, s23, v26
	s_nop 1
	v_cndmask_b32_e32 v19, 2, v19, vcc
	v_mul_i32_i24_e32 v20, 0xffffff7f, v19
	v_lshlrev_b32_e32 v19, 1, v19
	v_add_lshl_u32 v18, v20, v18, v19
	v_sub_u32_e32 v18, s18, v18
	v_cmp_lt_i32_e32 vcc, s26, v18
	v_cmp_gt_i32_e64 s[0:1], s17, v18
	s_and_saveexec_b64 s[14:15], s[0:1]
	s_xor_b64 s[0:1], exec, s[14:15]
	v_ashrrev_i32_e32 v19, 31, v18
	v_lshlrev_b64 v[20:21], 11, v[18:19]
	v_lshl_add_u64 v[22:23], v[194:195], 0, v[20:21]
	s_andn2_saveexec_b64 s[0:1], s[0:1]
	v_add_u32_e32 v19, 0xfffff800, v18
	v_mad_u64_u32 v[22:23], s[14:15], v19, s27, v[196:197]
	v_mov_b32_e32 v19, v157
	v_lshlrev_b64 v[20:21], 11, v[18:19]
	s_or_b64 exec, exec, s[0:1]
	v_lshl_add_u64 v[18:19], v[22:23], 0, s[28:29]
	v_lshl_add_u64 v[20:21], v[198:199], 0, v[20:21]
	v_min_i32_e32 v26, 0x187, v26
	v_cndmask_b32_e32 v29, v21, v19, vcc
	v_cndmask_b32_e32 v28, v20, v18, vcc
	global_load_dwordx4 v[18:21], v[22:23], off offset:16
	s_nop 0
	global_load_dwordx4 v[22:25], v[22:23], off
	s_nop 0
	global_load_dwordx4 v[82:85], v[28:29], off offset:16
	global_load_dwordx4 v[98:101], v[28:29], off
	v_ashrrev_i32_e32 v27, 31, v26
	v_lshl_add_u64 v[26:27], v[26:27], 2, s[30:31]
	global_load_dword v233, v[26:27], off
	v_add_u32_e32 v70, -8, v222
	v_min_i32_e32 v255, 0x187, v70
	v_lshl_add_u32 v255, v255, 2, s101
	ds_read_b32 v70, v255
	s_waitcnt lgkmcnt(0)
	v_cmp_lt_i32_e32 vcc, s19, v70
	v_min_i32_e32 v26, 0x182, v70
	s_nop 0
	v_cndmask_b32_e64 v27, 0, 1, vcc
	v_cmp_gt_i32_e32 vcc, s23, v70
	s_nop 1
	v_cndmask_b32_e32 v27, 2, v27, vcc
	v_mul_i32_i24_e32 v28, 0xffffff7f, v27
	v_lshlrev_b32_e32 v27, 1, v27
	v_add_lshl_u32 v26, v28, v26, v27
	v_sub_u32_e32 v26, s18, v26
	v_cmp_lt_i32_e32 vcc, s26, v26
	v_cmp_gt_i32_e64 s[0:1], s17, v26
	s_and_saveexec_b64 s[14:15], s[0:1]
	s_xor_b64 s[0:1], exec, s[14:15]
	v_ashrrev_i32_e32 v27, 31, v26
	v_lshlrev_b64 v[28:29], 11, v[26:27]
	v_lshl_add_u64 v[30:31], v[194:195], 0, v[28:29]
	s_andn2_saveexec_b64 s[0:1], s[0:1]
	v_add_u32_e32 v27, 0xfffff800, v26
	v_mad_u64_u32 v[30:31], s[14:15], v27, s27, v[196:197]
	v_mov_b32_e32 v27, v157
	v_lshlrev_b64 v[28:29], 11, v[26:27]
	s_or_b64 exec, exec, s[0:1]
	v_lshl_add_u64 v[26:27], v[30:31], 0, s[28:29]
	v_lshl_add_u64 v[28:29], v[198:199], 0, v[28:29]
	v_min_i32_e32 v70, 0x187, v70
	v_cndmask_b32_e32 v73, v29, v27, vcc
	v_cndmask_b32_e32 v72, v28, v26, vcc
	global_load_dwordx4 v[26:29], v[30:31], off offset:16
	s_nop 0
	global_load_dwordx4 v[30:33], v[30:31], off
	s_nop 0
	global_load_dwordx4 v[106:109], v[72:73], off offset:16
	global_load_dwordx4 v[130:133], v[72:73], off
	v_ashrrev_i32_e32 v71, 31, v70
	v_lshl_add_u64 v[70:71], v[70:71], 2, s[30:31]
	global_load_dword v234, v[70:71], off
	v_min_i32_e32 v255, 0x187, v222
	v_lshl_add_u32 v255, v255, 2, s101
	ds_read_b32 v254, v255
	s_waitcnt lgkmcnt(0)
	v_cmp_lt_i32_e32 vcc, s19, v254
	v_min_i32_e32 v70, 0x182, v254
	s_nop 0
	v_cndmask_b32_e64 v71, 0, 1, vcc
	v_cmp_gt_i32_e32 vcc, s23, v254
	s_nop 1
	v_cndmask_b32_e32 v71, 2, v71, vcc
	v_mul_i32_i24_e32 v72, 0xffffff7f, v71
	v_lshlrev_b32_e32 v71, 1, v71
	v_add_lshl_u32 v70, v72, v70, v71
	v_sub_u32_e32 v72, s18, v70
	v_cmp_lt_i32_e32 vcc, s26, v72
	v_cmp_gt_i32_e64 s[0:1], s17, v72
	s_and_saveexec_b64 s[14:15], s[0:1]
	s_xor_b64 s[0:1], exec, s[14:15]
	v_ashrrev_i32_e32 v73, 31, v72
	v_lshlrev_b64 v[70:71], 11, v[72:73]
	v_lshl_add_u64 v[74:75], v[194:195], 0, v[70:71]
	s_andn2_saveexec_b64 s[0:1], s[0:1]
	v_add_u32_e32 v70, 0xfffff800, v72
	v_mov_b32_e32 v73, v157
	v_mad_u64_u32 v[74:75], s[14:15], v70, s27, v[196:197]
	v_lshlrev_b64 v[70:71], 11, v[72:73]
	s_or_b64 exec, exec, s[0:1]
	v_add_f32_e32 v72, v235, v236
	v_add_f32_e32 v73, v227, v72
	v_max_f32_e32 v72, v224, v224
	v_max_f32_e32 v156, v72, v73
	v_sub_f32_e32 v73, v73, v156
	v_mul_f32_e32 v73, 0x3fb8aa3b, v73
	v_sub_f32_e32 v72, v224, v156
	v_exp_f32_e32 v224, v73
	v_add_f32_e32 v73, v237, v238
	v_add_f32_e32 v73, v226, v73
	v_max_f32_e32 v227, v156, v73
	v_sub_f32_e32 v73, v73, v227
	v_mul_f32_e32 v73, 0x3fb8aa3b, v73
	v_sub_f32_e32 v156, v156, v227
	v_exp_f32_e32 v236, v73
	v_add_f32_e32 v73, v239, v240
	v_mul_f32_e32 v156, 0x3fb8aa3b, v156
	v_add_f32_e32 v73, v225, v73
	v_mul_f32_e32 v72, 0x3fb8aa3b, v72
	v_exp_f32_e32 v226, v156
	v_max_f32_e32 v156, v227, v73
	v_exp_f32_e32 v72, v72
	v_sub_f32_e32 v225, v227, v156
	v_sub_f32_e32 v73, v73, v156
	v_mul_f32_e32 v225, 0x3fb8aa3b, v225
	v_mul_f32_e32 v73, 0x3fb8aa3b, v73
	v_exp_f32_e32 v238, v225
	v_exp_f32_e32 v240, v73
	v_fma_f32 v73, v223, v72, v224
	v_fma_f32 v73, v73, v226, v236
	v_pk_mul_f32 v[50:51], v[50:51], v[236:237] op_sel_hi:[1,0]
	v_fma_f32 v223, v73, v238, v240
	v_add_f32_e32 v73, v76, v77
	s_waitcnt vmcnt(35)
; __device__ __forceinline__ void p_attn_sample(const float* P, const float* ck, const float* cv, const float* relb, bf16* heads, const float* sbt, unsigned* qctr, volatile LAS unsigned* slot, int wave, int lane_in) {
;     ...
;         SLOADB(ak0, ak1, av0, av1, ab, 0)
; #pragma unroll 1
;         for (int it0 = 0; it0 < 48; it0 += 8) {
;             SLOADB(bk0, bk1, bv0, bv1, bbv, it0 + 4)
;             SPROCB(ak0, ak1, av0, av1, ab)
;             SLOADB(ak0, ak1, av0, av1, ab, it0 + 8)
;             SPROCB(bk0, bk1, bv0, bv1, bbv)
	v_add_f32_e32 v73, v221, v73
	v_max_f32_e32 v225, v156, v73
	v_sub_f32_e32 v73, v73, v225
	v_sub_f32_e32 v76, v156, v225
	v_mul_f32_e32 v73, 0x3fb8aa3b, v73
	v_mul_f32_e32 v76, 0x3fb8aa3b, v76
	v_exp_f32_e32 v156, v73
	v_exp_f32_e32 v242, v76
	v_pk_mul_f32 v[42:43], v[42:43], v[224:225] op_sel_hi:[1,0]
	s_add_i32 s3, s3, 8
	v_pk_fma_f32 v[42:43], v[218:219], v[72:73], v[42:43] op_sel_hi:[1,0,1]
	v_pk_mul_f32 v[6:7], v[6:7], v[156:157] op_sel_hi:[1,0]
	v_pk_fma_f32 v[42:43], v[42:43], v[226:227], v[50:51] op_sel_hi:[1,0,1]
	v_pk_mul_f32 v[50:51], v[58:59], v[240:241] op_sel_hi:[1,0]
	v_pk_mul_f32 v[8:9], v[8:9], v[156:157] op_sel_hi:[1,0]
	v_pk_fma_f32 v[42:43], v[42:43], v[238:239], v[50:51] op_sel_hi:[1,0,1]
	v_pk_mul_f32 v[2:3], v[2:3], v[156:157] op_sel_hi:[1,0]
	v_pk_fma_f32 v[42:43], v[42:43], v[242:243], v[6:7] op_sel_hi:[1,0,1]
	v_pk_mul_f32 v[6:7], v[44:45], v[224:225] op_sel_hi:[1,0]
	v_pk_mul_f32 v[44:45], v[52:53], v[236:237] op_sel_hi:[1,0]
	v_pk_fma_f32 v[6:7], v[216:217], v[72:73], v[6:7] op_sel_hi:[1,0,1]
	v_pk_mul_f32 v[4:5], v[4:5], v[156:157] op_sel_hi:[1,0]
	v_pk_fma_f32 v[6:7], v[6:7], v[226:227], v[44:45] op_sel_hi:[1,0,1]
	v_pk_mul_f32 v[44:45], v[60:61], v[240:241] op_sel_hi:[1,0]
	v_fmac_f32_e32 v156, v223, v242
	v_pk_fma_f32 v[6:7], v[6:7], v[238:239], v[44:45] op_sel_hi:[1,0,1]
	s_cmp_gt_u32 s3, 39
	v_pk_fma_f32 v[44:45], v[6:7], v[242:243], v[8:9] op_sel_hi:[1,0,1]
	v_pk_mul_f32 v[6:7], v[34:35], v[224:225] op_sel_hi:[1,0]
	v_pk_mul_f32 v[8:9], v[38:39], v[236:237] op_sel_hi:[1,0]
	v_pk_fma_f32 v[6:7], v[212:213], v[72:73], v[6:7] op_sel_hi:[1,0,1]
	v_min_i32_e32 v38, 0x187, v254
	v_pk_fma_f32 v[6:7], v[6:7], v[226:227], v[8:9] op_sel_hi:[1,0,1]
	v_pk_mul_f32 v[8:9], v[46:47], v[240:241] op_sel_hi:[1,0]
	v_ashrrev_i32_e32 v39, 31, v38
	v_pk_fma_f32 v[6:7], v[6:7], v[238:239], v[8:9] op_sel_hi:[1,0,1]
	v_lshl_add_u64 v[38:39], v[38:39], 2, s[30:31]
	v_pk_fma_f32 v[34:35], v[6:7], v[242:243], v[2:3] op_sel_hi:[1,0,1]
	v_pk_mul_f32 v[2:3], v[36:37], v[224:225] op_sel_hi:[1,0]
	v_pk_mul_f32 v[6:7], v[40:41], v[236:237] op_sel_hi:[1,0]
	v_pk_fma_f32 v[2:3], v[214:215], v[72:73], v[2:3] op_sel_hi:[1,0,1]
	s_waitcnt vmcnt(33)
	v_pk_mul_f32 v[40:41], v[204:205], v[114:115]
	v_pk_fma_f32 v[2:3], v[2:3], v[226:227], v[6:7] op_sel_hi:[1,0,1]
	v_pk_mul_f32 v[6:7], v[48:49], v[240:241] op_sel_hi:[1,0]
	v_add_u32_e32 v222, 64, v222
	v_pk_fma_f32 v[2:3], v[2:3], v[238:239], v[6:7] op_sel_hi:[1,0,1]
	s_nop 0
	v_pk_fma_f32 v[36:37], v[2:3], v[242:243], v[4:5] op_sel_hi:[1,0,1]
	v_lshl_add_u64 v[2:3], v[74:75], 0, s[28:29]
	v_lshl_add_u64 v[4:5], v[198:199], 0, v[70:71]
	v_cndmask_b32_e32 v7, v5, v3, vcc
	v_cndmask_b32_e32 v6, v4, v2, vcc
	global_load_dwordx4 v[70:73], v[74:75], off offset:16
	s_nop 0
	global_load_dwordx4 v[74:77], v[74:75], off
	s_nop 0
	global_load_dwordx4 v[2:5], v[6:7], off offset:16
	s_nop 0
	global_load_dwordx4 v[6:9], v[6:7], off
	s_nop 0
	global_load_dword v221, v[38:39], off
	v_pk_mul_f32 v[38:39], v[206:207], v[116:117]
	s_nop 0
	v_pk_mov_b32 v[46:47], v[40:41], v[38:39] op_sel:[1,0]
	v_mov_b32_e32 v41, v39
	v_pk_add_f32 v[38:39], v[46:47], v[40:41]
	v_pk_mul_f32 v[40:41], v[202:203], v[104:105]
	v_pk_mul_f32 v[46:47], v[200:201], v[102:103]
	v_mov_b32_e32 v48, v40
	v_mov_b32_e32 v49, v46
	v_mov_b32_e32 v46, v41
	v_pk_add_f32 v[40:41], v[48:49], v[46:47]
	v_add_f32_e32 v38, v38, v39
	v_add_f32_e32 v38, v38, v41
	v_add_f32_e32 v38, v40, v38
	s_waitcnt vmcnt(33)
	v_pk_mul_f32 v[46:47], v[206:207], v[124:125]
	v_pk_mul_f32 v[48:49], v[204:205], v[122:123]
	v_add_f32_dpp v38, v38, v38 quad_perm:[1,0,3,2] row_mask:0xf bank_mask:0xf bound_ctrl:1
	v_pk_mov_b32 v[50:51], v[48:49], v[46:47] op_sel:[1,0]
	v_mov_b32_e32 v49, v47
	v_add_f32_dpp v38, v38, v38 quad_perm:[2,3,0,1] row_mask:0xf bank_mask:0xf bound_ctrl:1
	v_pk_add_f32 v[46:47], v[50:51], v[48:49]
	v_pk_mul_f32 v[48:49], v[202:203], v[120:121]
	v_add_f32_dpp v38, v38, v38 row_half_mirror row_mask:0xf bank_mask:0xf bound_ctrl:1
	v_add_f32_e32 v39, v228, v38
	v_max_f32_e32 v41, v225, v39
	v_sub_f32_e32 v39, v39, v41
	v_pk_mul_f32 v[50:51], v[200:201], v[118:119]
	v_mul_f32_e32 v39, 0x3fb8aa3b, v39
	v_mov_b32_e32 v52, v48
	v_mov_b32_e32 v53, v50
	v_mov_b32_e32 v50, v49
	v_exp_f32_e32 v40, v39
	v_pk_add_f32 v[48:49], v[52:53], v[50:51]
	v_add_f32_e32 v39, v46, v47
	v_add_f32_e32 v39, v39, v49
	v_add_f32_e32 v39, v48, v39
	s_waitcnt vmcnt(28)
	v_pk_mul_f32 v[50:51], v[206:207], v[140:141]
	v_pk_mul_f32 v[52:53], v[204:205], v[138:139]
	v_add_f32_dpp v39, v39, v39 quad_perm:[1,0,3,2] row_mask:0xf bank_mask:0xf bound_ctrl:1
	v_pk_mov_b32 v[58:59], v[52:53], v[50:51] op_sel:[1,0]
	v_mov_b32_e32 v53, v51
	v_add_f32_dpp v39, v39, v39 quad_perm:[2,3,0,1] row_mask:0xf bank_mask:0xf bound_ctrl:1
	v_pk_add_f32 v[50:51], v[58:59], v[52:53]
	v_pk_mul_f32 v[52:53], v[202:203], v[136:137]
	v_add_f32_dpp v39, v39, v39 row_half_mirror row_mask:0xf bank_mask:0xf bound_ctrl:1
	v_add_f32_e32 v39, v229, v39
	v_max_f32_e32 v47, v41, v39
	v_sub_f32_e32 v39, v39, v47
	v_pk_mul_f32 v[58:59], v[200:201], v[134:135]
	v_mul_f32_e32 v39, 0x3fb8aa3b, v39
	v_mov_b32_e32 v60, v52
	v_mov_b32_e32 v61, v58
	v_mov_b32_e32 v58, v53
	v_exp_f32_e32 v48, v39
	v_pk_add_f32 v[52:53], v[60:61], v[58:59]
	v_add_f32_e32 v39, v50, v51
	v_add_f32_e32 v39, v39, v53
	v_add_f32_e32 v39, v52, v39
	v_sub_f32_e32 v38, v225, v41
	v_sub_f32_e32 v41, v41, v47
	v_add_f32_dpp v39, v39, v39 quad_perm:[1,0,3,2] row_mask:0xf bank_mask:0xf bound_ctrl:1
	v_mul_f32_e32 v41, 0x3fb8aa3b, v41
	s_waitcnt vmcnt(23)
; __device__ __forceinline__ void p_attn_sample(const float* P, const float* ck, const float* cv, const float* relb, bf16* heads, const float* sbt, unsigned* qctr, volatile LAS unsigned* slot, int wave, int lane_in) {
;     ...
;         SLOADB(ak0, ak1, av0, av1, ab, 0)
; #pragma unroll 1
;         for (int it0 = 0; it0 < 48; it0 += 8) {
;             SLOADB(bk0, bk1, bv0, bv1, bbv, it0 + 4)
;             SPROCB(ak0, ak1, av0, av1, ab)
;             SLOADB(ak0, ak1, av0, av1, ab, it0 + 8)
;             SPROCB(bk0, bk1, bv0, bv1, bbv)
	v_pk_mul_f32 v[58:59], v[206:207], v[148:149]
	v_add_f32_dpp v39, v39, v39 quad_perm:[2,3,0,1] row_mask:0xf bank_mask:0xf bound_ctrl:1
	v_pk_mul_f32 v[60:61], v[204:205], v[146:147]
	v_exp_f32_e32 v46, v41
	v_add_f32_dpp v39, v39, v39 row_half_mirror row_mask:0xf bank_mask:0xf bound_ctrl:1
	v_add_f32_e32 v39, v230, v39
	v_max_f32_e32 v41, v47, v39
	v_pk_mov_b32 v[102:103], v[60:61], v[58:59] op_sel:[1,0]
	v_mov_b32_e32 v61, v59
	v_sub_f32_e32 v39, v39, v41
	v_pk_add_f32 v[58:59], v[102:103], v[60:61]
	v_pk_mul_f32 v[60:61], v[202:203], v[144:145]
	v_pk_mul_f32 v[102:103], v[200:201], v[142:143]
	v_mul_f32_e32 v39, 0x3fb8aa3b, v39
	v_mov_b32_e32 v104, v60
	v_mov_b32_e32 v105, v102
	v_mov_b32_e32 v102, v61
	v_exp_f32_e32 v52, v39
	v_pk_add_f32 v[60:61], v[104:105], v[102:103]
	v_add_f32_e32 v39, v58, v59
	v_add_f32_e32 v39, v39, v61
	v_add_f32_e32 v39, v60, v39
	v_mul_f32_e32 v38, 0x3fb8aa3b, v38
	v_exp_f32_e32 v38, v38
	v_add_f32_dpp v39, v39, v39 quad_perm:[1,0,3,2] row_mask:0xf bank_mask:0xf bound_ctrl:1
	v_sub_f32_e32 v47, v47, v41
	v_mul_f32_e32 v47, 0x3fb8aa3b, v47
	v_add_f32_dpp v39, v39, v39 quad_perm:[2,3,0,1] row_mask:0xf bank_mask:0xf bound_ctrl:1
	v_exp_f32_e32 v50, v47
	s_nop 0
	v_add_f32_dpp v39, v39, v39 row_half_mirror row_mask:0xf bank_mask:0xf bound_ctrl:1
	s_waitcnt vmcnt(20)
	v_add_f32_e32 v39, v231, v39
	v_max_f32_e32 v224, v41, v39
	v_sub_f32_e32 v39, v39, v224
	v_mul_f32_e32 v39, 0x3fb8aa3b, v39
	v_sub_f32_e32 v41, v41, v224
	v_exp_f32_e32 v60, v39
	v_fma_f32 v39, v156, v38, v40
	v_mul_f32_e32 v41, 0x3fb8aa3b, v41
	v_fma_f32 v39, v39, v46, v48
	v_exp_f32_e32 v58, v41
	v_fma_f32 v39, v39, v50, v52
	v_pk_mul_f32 v[62:63], v[62:63], v[40:41] op_sel_hi:[1,0]
	v_fma_f32 v223, v39, v58, v60
	v_pk_fma_f32 v[42:43], v[42:43], v[38:39], v[62:63] op_sel_hi:[1,0,1]
	v_pk_mul_f32 v[62:63], v[78:79], v[48:49] op_sel_hi:[1,0]
	s_nop 0
	v_pk_fma_f32 v[42:43], v[42:43], v[46:47], v[62:63] op_sel_hi:[1,0,1]
	v_pk_mul_f32 v[62:63], v[94:95], v[52:53] op_sel_hi:[1,0]
	s_nop 0
	v_pk_fma_f32 v[42:43], v[42:43], v[50:51], v[62:63] op_sel_hi:[1,0,1]
	v_pk_mul_f32 v[62:63], v[126:127], v[60:61] op_sel_hi:[1,0]
	s_nop 0
	v_pk_fma_f32 v[218:219], v[42:43], v[58:59], v[62:63] op_sel_hi:[1,0,1]
	v_pk_mul_f32 v[42:43], v[64:65], v[40:41] op_sel_hi:[1,0]
	s_nop 0
	v_pk_fma_f32 v[42:43], v[44:45], v[38:39], v[42:43] op_sel_hi:[1,0,1]
	v_pk_mul_f32 v[44:45], v[80:81], v[48:49] op_sel_hi:[1,0]
	s_nop 0
	v_pk_fma_f32 v[42:43], v[42:43], v[46:47], v[44:45] op_sel_hi:[1,0,1]
	v_pk_mul_f32 v[44:45], v[96:97], v[52:53] op_sel_hi:[1,0]
	s_nop 0
	v_pk_fma_f32 v[42:43], v[42:43], v[50:51], v[44:45] op_sel_hi:[1,0,1]
	v_pk_mul_f32 v[44:45], v[128:129], v[60:61] op_sel_hi:[1,0]
	s_nop 0
	v_pk_fma_f32 v[216:217], v[42:43], v[58:59], v[44:45] op_sel_hi:[1,0,1]
	v_pk_mul_f32 v[42:43], v[54:55], v[40:41] op_sel_hi:[1,0]
	s_nop 0
	v_pk_fma_f32 v[34:35], v[34:35], v[38:39], v[42:43] op_sel_hi:[1,0,1]
	v_pk_mul_f32 v[42:43], v[66:67], v[48:49] op_sel_hi:[1,0]
	s_nop 0
	v_pk_fma_f32 v[34:35], v[34:35], v[46:47], v[42:43] op_sel_hi:[1,0,1]
	v_pk_mul_f32 v[42:43], v[86:87], v[52:53] op_sel_hi:[1,0]
	s_nop 0
	v_pk_fma_f32 v[34:35], v[34:35], v[50:51], v[42:43] op_sel_hi:[1,0,1]
	v_pk_mul_f32 v[42:43], v[110:111], v[60:61] op_sel_hi:[1,0]
	s_nop 0
	v_pk_fma_f32 v[212:213], v[34:35], v[58:59], v[42:43] op_sel_hi:[1,0,1]
	v_pk_mul_f32 v[34:35], v[56:57], v[40:41] op_sel_hi:[1,0]
	s_nop 0
	v_pk_fma_f32 v[34:35], v[36:37], v[38:39], v[34:35] op_sel_hi:[1,0,1]
	v_pk_mul_f32 v[36:37], v[68:69], v[48:49] op_sel_hi:[1,0]
	s_nop 0
	v_pk_fma_f32 v[34:35], v[34:35], v[46:47], v[36:37] op_sel_hi:[1,0,1]
	v_pk_mul_f32 v[36:37], v[88:89], v[52:53] op_sel_hi:[1,0]
	s_nop 0
	v_pk_fma_f32 v[34:35], v[34:35], v[50:51], v[36:37] op_sel_hi:[1,0,1]
	v_pk_mul_f32 v[36:37], v[112:113], v[60:61] op_sel_hi:[1,0]
	s_nop 0
	v_pk_fma_f32 v[214:215], v[34:35], v[58:59], v[36:37] op_sel_hi:[1,0,1]
	s_cbranch_scc1 .LBB0_1417
	s_waitcnt vmcnt(17)
	v_mov_b64_e32 v[34:35], v[90:91]
	s_waitcnt vmcnt(12)
	v_mov_b64_e32 v[38:39], v[82:83]
	s_waitcnt vmcnt(7)
	v_mov_b64_e32 v[46:47], v[106:107]
	v_mov_b64_e32 v[42:43], v[150:151]
	v_mov_b64_e32 v[50:51], v[98:99]
	s_waitcnt vmcnt(6)
	v_mov_b64_e32 v[58:59], v[130:131]
	v_mov_b64_e32 v[36:37], v[92:93]
	v_mov_b64_e32 v[40:41], v[84:85]
	v_mov_b64_e32 v[48:49], v[108:109]
	v_mov_b64_e32 v[44:45], v[152:153]
	v_mov_b64_e32 v[52:53], v[100:101]
	v_mov_b64_e32 v[60:61], v[132:133]
	s_waitcnt vmcnt(5)
	v_mov_b32_e32 v225, v234
	v_mov_b32_e32 v226, v233
	v_mov_b32_e32 v227, v232
	s_branch .LBB0_1383
